# stack: attention (staging strides, ballot, first-tile split of shift test, interleaved row-max chains, scalar row-sum adds, hoisted K fragment reads) + GEMM SALU M0
# speedup vs baseline: 1.0310x; 1.0027x over previous
.LBB0_882:
	v_mad_u32_u24 v212, v203, s82, v201
	ds_read_b128 v[64:67], v212
	ds_read_b128 v[204:207], v212 offset:32
	s_mov_b64 s[28:29], 0
	ds_read_b128 v[208:211], v212 offset:64
	ds_read_b128 v[246:249], v212 offset:96
	s_waitcnt lgkmcnt(2)
	v_mfma_f32_32x32x16_bf16 v[80:95], v[64:67], v[96:99], 0
	v_mfma_f32_32x32x16_bf16 v[64:79], v[64:67], v[136:139], 0
	v_mfma_f32_32x32x16_bf16 v[80:95], v[204:207], v[100:103], v[80:95]
	v_mfma_f32_32x32x16_bf16 v[64:79], v[204:207], v[120:123], v[64:79]
	ds_read_b128 v[204:207], v212 offset:128
	ds_read_b128 v[250:253], v212 offset:160
	s_waitcnt lgkmcnt(2)
	v_mfma_f32_32x32x16_bf16 v[80:95], v[208:211], v[104:107], v[80:95]
	v_mfma_f32_32x32x16_bf16 v[64:79], v[208:211], v[124:127], v[64:79]
	v_mfma_f32_32x32x16_bf16 v[80:95], v[246:249], v[108:111], v[80:95]
	v_mfma_f32_32x32x16_bf16 v[64:79], v[246:249], v[128:131], v[64:79]
	s_waitcnt lgkmcnt(0)
	v_mfma_f32_32x32x16_bf16 v[80:95], v[204:207], v[112:115], v[80:95]
	v_mfma_f32_32x32x16_bf16 v[64:79], v[204:207], v[132:135], v[64:79]
	v_mfma_f32_32x32x16_bf16 v[80:95], v[250:253], v[116:119], v[80:95]
	v_mfma_f32_32x32x16_bf16 v[64:79], v[250:253], v[140:143], v[64:79]

.LBB0_885:
	s_nop 10
	v_max_f32_e32 v203, v80, v81
	v_max_f32_e32 v205, v64, v65
	v_max3_f32 v203, v203, v82, v83
	v_max3_f32 v205, v205, v66, v67
	v_max3_f32 v203, v203, v84, v85
	v_max3_f32 v205, v205, v68, v69
	v_max3_f32 v203, v203, v86, v87
	v_max3_f32 v205, v205, v70, v71
	v_max3_f32 v203, v203, v88, v89
	v_max3_f32 v205, v205, v72, v73
	v_max3_f32 v203, v203, v90, v91
	v_max3_f32 v205, v205, v74, v75
	v_max3_f32 v203, v203, v92, v93
	v_max3_f32 v205, v205, v76, v77
	v_max3_f32 v203, v203, v94, v95
	v_max3_f32 v205, v205, v78, v79
	v_mov_b32_e32 v204, v203
	v_mov_b32_e32 v206, v205
	s_nop 1
	v_permlane32_swap_b32_e32 v203, v204
	v_permlane32_swap_b32_e32 v205, v206
	v_max_f32_e32 v204, v203, v204
	v_max_f32_e32 v203, v205, v206
	v_max_f32_e32 v205, v204, v203
	v_cmp_lt_f32_e32 vcc, s83, v205
	s_cmp_lg_u64 s[64:65], 0
	s_cbranch_scc1 .Lhwat0_firstchk
	s_cbranch_vccz .LBB0_887
	s_branch .Lhwat0_rare
.Lhwat0_firstchk:
	v_min_f32_e32 v205, v204, v203
	v_cmp_gt_f32_e64 s[28:29], s84, v205
	s_or_b64 s[28:29], vcc, s[28:29]
	s_and_b64 vcc, exec, s[28:29]
	s_cbranch_vccz .LBB0_887
.Lhwat0_rare:
	v_max_f32_e32 v205, v204, v204
	v_max_f32_e32 v205, 0, v205
	v_cndmask_b32_e64 v204, v205, v204, s[64:65]
	v_exp_f32_e64 v206, -v204
	v_add_f32_e32 v199, v199, v204
	v_pk_add_f32 v[80:81], v[80:81], v[204:205] op_sel_hi:[1,0] neg_lo:[0,1] neg_hi:[0,1]
	v_pk_add_f32 v[82:83], v[82:83], v[204:205] op_sel_hi:[1,0] neg_lo:[0,1] neg_hi:[0,1]
	v_pk_add_f32 v[84:85], v[84:85], v[204:205] op_sel_hi:[1,0] neg_lo:[0,1] neg_hi:[0,1]
	v_pk_add_f32 v[86:87], v[86:87], v[204:205] op_sel_hi:[1,0] neg_lo:[0,1] neg_hi:[0,1]
	v_pk_add_f32 v[88:89], v[88:89], v[204:205] op_sel_hi:[1,0] neg_lo:[0,1] neg_hi:[0,1]
	v_pk_add_f32 v[90:91], v[90:91], v[204:205] op_sel_hi:[1,0] neg_lo:[0,1] neg_hi:[0,1]
	v_pk_add_f32 v[92:93], v[92:93], v[204:205] op_sel_hi:[1,0] neg_lo:[0,1] neg_hi:[0,1]
	v_pk_add_f32 v[94:95], v[94:95], v[204:205] op_sel_hi:[1,0] neg_lo:[0,1] neg_hi:[0,1]
	v_max_f32_e32 v204, v203, v203
	v_max_f32_e32 v204, 0, v204
	v_cndmask_b32_e64 v204, v204, v203, s[64:65]
	v_exp_f32_e64 v208, -v204
	v_mov_b32_e32 v209, v206
	v_pk_mul_f32 v[62:63], v[62:63], v[206:207] op_sel_hi:[1,0]
	v_pk_mul_f32 v[60:61], v[60:61], v[206:207] op_sel_hi:[1,0]
	v_pk_mul_f32 v[58:59], v[58:59], v[206:207] op_sel_hi:[1,0]
	v_pk_mul_f32 v[56:57], v[56:57], v[206:207] op_sel_hi:[1,0]
	v_pk_mul_f32 v[54:55], v[54:55], v[206:207] op_sel_hi:[1,0]
	v_pk_mul_f32 v[52:53], v[52:53], v[206:207] op_sel_hi:[1,0]
	v_pk_mul_f32 v[50:51], v[50:51], v[206:207] op_sel_hi:[1,0]
	v_pk_mul_f32 v[48:49], v[48:49], v[206:207] op_sel_hi:[1,0]
	v_pk_mul_f32 v[46:47], v[46:47], v[206:207] op_sel_hi:[1,0]
	v_pk_mul_f32 v[44:45], v[44:45], v[206:207] op_sel_hi:[1,0]
	v_pk_mul_f32 v[42:43], v[42:43], v[206:207] op_sel_hi:[1,0]
	v_pk_mul_f32 v[40:41], v[40:41], v[206:207] op_sel_hi:[1,0]
	v_pk_mul_f32 v[38:39], v[38:39], v[206:207] op_sel_hi:[1,0]
	v_pk_mul_f32 v[36:37], v[36:37], v[206:207] op_sel_hi:[1,0]
	v_pk_mul_f32 v[34:35], v[34:35], v[206:207] op_sel_hi:[1,0]
	v_pk_mul_f32 v[32:33], v[32:33], v[206:207] op_sel_hi:[1,0]
	v_add_f32_e32 v200, v200, v204
	v_pk_mul_f32 v[150:151], v[150:151], v[208:209]
	v_pk_add_f32 v[64:65], v[64:65], v[204:205] op_sel_hi:[1,0] neg_lo:[0,1] neg_hi:[0,1]
	v_pk_add_f32 v[66:67], v[66:67], v[204:205] op_sel_hi:[1,0] neg_lo:[0,1] neg_hi:[0,1]
	v_pk_add_f32 v[68:69], v[68:69], v[204:205] op_sel_hi:[1,0] neg_lo:[0,1] neg_hi:[0,1]
	v_pk_add_f32 v[70:71], v[70:71], v[204:205] op_sel_hi:[1,0] neg_lo:[0,1] neg_hi:[0,1]
	v_pk_add_f32 v[72:73], v[72:73], v[204:205] op_sel_hi:[1,0] neg_lo:[0,1] neg_hi:[0,1]
	v_pk_add_f32 v[74:75], v[74:75], v[204:205] op_sel_hi:[1,0] neg_lo:[0,1] neg_hi:[0,1]
	v_pk_add_f32 v[76:77], v[76:77], v[204:205] op_sel_hi:[1,0] neg_lo:[0,1] neg_hi:[0,1]
	v_pk_add_f32 v[78:79], v[78:79], v[204:205] op_sel_hi:[1,0] neg_lo:[0,1] neg_hi:[0,1]
	v_pk_mul_f32 v[30:31], v[30:31], v[208:209] op_sel_hi:[1,0]
	v_pk_mul_f32 v[28:29], v[28:29], v[208:209] op_sel_hi:[1,0]
	v_pk_mul_f32 v[26:27], v[26:27], v[208:209] op_sel_hi:[1,0]
	v_pk_mul_f32 v[24:25], v[24:25], v[208:209] op_sel_hi:[1,0]
	v_pk_mul_f32 v[22:23], v[22:23], v[208:209] op_sel_hi:[1,0]
	v_pk_mul_f32 v[20:21], v[20:21], v[208:209] op_sel_hi:[1,0]
	v_pk_mul_f32 v[18:19], v[18:19], v[208:209] op_sel_hi:[1,0]
	v_pk_mul_f32 v[16:17], v[16:17], v[208:209] op_sel_hi:[1,0]
	v_pk_mul_f32 v[14:15], v[14:15], v[208:209] op_sel_hi:[1,0]
	v_pk_mul_f32 v[12:13], v[12:13], v[208:209] op_sel_hi:[1,0]
	v_pk_mul_f32 v[10:11], v[10:11], v[208:209] op_sel_hi:[1,0]
	v_pk_mul_f32 v[8:9], v[8:9], v[208:209] op_sel_hi:[1,0]
	v_pk_mul_f32 v[6:7], v[6:7], v[208:209] op_sel_hi:[1,0]
	v_pk_mul_f32 v[4:5], v[4:5], v[208:209] op_sel_hi:[1,0]
	v_pk_mul_f32 v[2:3], v[2:3], v[208:209] op_sel_hi:[1,0]
	v_pk_mul_f32 v[0:1], v[0:1], v[208:209] op_sel_hi:[1,0]
	s_mov_b64 s[62:63], -1
.LBB0_887:
	v_lshl_add_u32 v203, s68, 6, v202
	v_exp_f32_e32 v209, v80
	v_exp_f32_e32 v211, v81
	v_exp_f32_e32 v213, v82
	v_exp_f32_e32 v215, v83
	ds_read_b128 v[80:83], v203 offset:13312
	ds_read_b128 v[204:207], v203 offset:17920
	v_exp_f32_e32 v217, v84
	v_exp_f32_e32 v219, v85
	v_exp_f32_e32 v221, v86
	v_exp_f32_e32 v223, v87
	v_exp_f32_e32 v208, v64
	v_exp_f32_e32 v210, v65
	v_exp_f32_e32 v212, v66
	v_exp_f32_e32 v214, v67
	v_exp_f32_e32 v216, v68
	v_exp_f32_e32 v218, v69
	v_exp_f32_e32 v220, v70
	v_exp_f32_e32 v222, v71
	v_cvt_pk_bf16_f32 v64, v209, v211
	v_cvt_pk_bf16_f32 v65, v213, v215
	v_cvt_pk_bf16_f32 v66, v217, v219
	v_cvt_pk_bf16_f32 v67, v221, v223
	v_cvt_pk_bf16_f32 v68, v208, v210
	v_cvt_pk_bf16_f32 v69, v212, v214
	v_cvt_pk_bf16_f32 v70, v216, v218
	v_cvt_pk_bf16_f32 v71, v220, v222
	ds_read_b128 v[84:87], v203 offset:13344
	s_waitcnt lgkmcnt(0)
	v_mfma_f32_32x32x16_bf16 v[48:63], v[80:83], v[64:67], v[48:63]
	v_exp_f32_e32 v225, v88
	v_exp_f32_e32 v224, v72
	v_exp_f32_e32 v88, v73
	v_exp_f32_e32 v89, v89
	v_exp_f32_e32 v227, v90
	v_exp_f32_e32 v91, v91
	v_exp_f32_e32 v229, v92
	v_mfma_f32_32x32x16_bf16 v[16:31], v[80:83], v[68:71], v[16:31]
	ds_read_b128 v[80:83], v203 offset:17952
	v_exp_f32_e32 v93, v93
	v_exp_f32_e32 v231, v94
	v_exp_f32_e32 v95, v95
	v_exp_f32_e32 v226, v74
	v_exp_f32_e32 v90, v75
	v_exp_f32_e32 v228, v76
	v_mfma_f32_32x32x16_bf16 v[32:47], v[204:207], v[64:67], v[32:47]
	v_exp_f32_e32 v92, v77
	v_add_f32_e32 v64, v210, v208
	v_add_f32_e32 v65, v211, v209
	v_exp_f32_e32 v230, v78
	v_add_f32_e32 v208, v212, v64
	v_add_f32_e32 v209, v213, v65
	v_exp_f32_e32 v94, v79
	v_add_f32_e32 v72, v214, v208
	v_add_f32_e32 v73, v215, v209
	v_mfma_f32_32x32x16_bf16 v[0:15], v[204:207], v[68:71], v[0:15]
	v_add_f32_e64 v72, v216, v72
	v_add_f32_e64 v73, v217, v73
	v_cvt_pk_bf16_f32 v64, v225, v89
	v_add_f32_e64 v72, v218, v72
	v_add_f32_e64 v73, v219, v73
	v_cvt_pk_bf16_f32 v65, v227, v91
	v_add_f32_e32 v72, v220, v72
	v_add_f32_e32 v73, v221, v73
	v_cvt_pk_bf16_f32 v66, v229, v93
	v_add_f32_e32 v72, v222, v72
	v_add_f32_e32 v73, v223, v73
	v_cvt_pk_bf16_f32 v67, v231, v95
	v_cvt_pk_bf16_f32 v68, v224, v88
	v_cvt_pk_bf16_f32 v69, v226, v90
	v_cvt_pk_bf16_f32 v70, v228, v92
	v_cvt_pk_bf16_f32 v71, v230, v94
	v_add_f32_e32 v72, v224, v72
	v_add_f32_e32 v73, v225, v73
	v_mfma_f32_32x32x16_bf16 v[48:63], v[84:87], v[64:67], v[48:63]
	v_add_f32_e64 v72, v88, v72
	v_add_f32_e64 v73, v89, v73
	s_xor_b64 s[28:29], s[66:67], -1
	s_mov_b32 s68, 1
	s_mov_b64 s[66:67], 0
	s_and_b64 vcc, exec, s[28:29]
	v_mfma_f32_32x32x16_bf16 v[16:31], v[84:87], v[68:71], v[16:31]
	s_waitcnt lgkmcnt(0)
	v_mfma_f32_32x32x16_bf16 v[32:47], v[80:83], v[64:67], v[32:47]
	v_add_f32_e64 v64, v226, v72
	v_add_f32_e64 v65, v227, v73
	v_add_f32_e64 v64, v90, v64
	v_add_f32_e64 v65, v91, v65
	v_add_f32_e64 v64, v228, v64
	v_add_f32_e64 v65, v229, v65
	v_add_f32_e32 v64, v92, v64
	v_add_f32_e32 v65, v93, v65
	v_mfma_f32_32x32x16_bf16 v[0:15], v[80:83], v[68:71], v[0:15]
	v_add_f32_e64 v64, v230, v64
	v_add_f32_e64 v65, v231, v65
	v_add_f32_e64 v64, v94, v64
	v_add_f32_e64 v65, v95, v65
	v_add_f32_e64 v150, v150, v64
	v_add_f32_e64 v151, v151, v65
	s_cbranch_vccnz .LBB0_889
	s_mov_b64 s[64:65], 0
	s_and_b64 vcc, exec, s[62:63]
	v_lshl_or_b32 v203, s68, 5, v190
	s_mov_b64 s[28:29], -1
	s_cbranch_vccz .LBB0_882
	s_branch .LBB0_883

.LBB0_2116:
	v_mad_u32_u24 v212, v203, s81, v201
	ds_read_b128 v[64:67], v212
	ds_read_b128 v[204:207], v212 offset:32
	s_mov_b64 s[34:35], 0
	ds_read_b128 v[208:211], v212 offset:64
	ds_read_b128 v[246:249], v212 offset:96
	s_waitcnt lgkmcnt(2)
	v_mfma_f32_32x32x16_bf16 v[80:95], v[64:67], v[96:99], 0
	v_mfma_f32_32x32x16_bf16 v[64:79], v[64:67], v[136:139], 0
	v_mfma_f32_32x32x16_bf16 v[80:95], v[204:207], v[100:103], v[80:95]
	v_mfma_f32_32x32x16_bf16 v[64:79], v[204:207], v[120:123], v[64:79]
	ds_read_b128 v[204:207], v212 offset:128
	ds_read_b128 v[250:253], v212 offset:160
	s_waitcnt lgkmcnt(2)
	v_mfma_f32_32x32x16_bf16 v[80:95], v[208:211], v[104:107], v[80:95]
	v_mfma_f32_32x32x16_bf16 v[64:79], v[208:211], v[124:127], v[64:79]
	v_mfma_f32_32x32x16_bf16 v[80:95], v[246:249], v[108:111], v[80:95]
	v_mfma_f32_32x32x16_bf16 v[64:79], v[246:249], v[128:131], v[64:79]
	s_waitcnt lgkmcnt(0)
	v_mfma_f32_32x32x16_bf16 v[80:95], v[204:207], v[112:115], v[80:95]
	v_mfma_f32_32x32x16_bf16 v[64:79], v[204:207], v[132:135], v[64:79]
	v_mfma_f32_32x32x16_bf16 v[80:95], v[250:253], v[116:119], v[80:95]
	v_mfma_f32_32x32x16_bf16 v[64:79], v[250:253], v[140:143], v[64:79]

.LBB0_2119:
	s_nop 10
	v_max_f32_e32 v203, v80, v81
	v_max_f32_e32 v205, v64, v65
	v_max3_f32 v203, v203, v82, v83
	v_max3_f32 v205, v205, v66, v67
	v_max3_f32 v203, v203, v84, v85
	v_max3_f32 v205, v205, v68, v69
	v_max3_f32 v203, v203, v86, v87
	v_max3_f32 v205, v205, v70, v71
	v_max3_f32 v203, v203, v88, v89
	v_max3_f32 v205, v205, v72, v73
	v_max3_f32 v203, v203, v90, v91
	v_max3_f32 v205, v205, v74, v75
	v_max3_f32 v203, v203, v92, v93
	v_max3_f32 v205, v205, v76, v77
	v_max3_f32 v203, v203, v94, v95
	v_max3_f32 v205, v205, v78, v79
	v_mov_b32_e32 v204, v203
	v_mov_b32_e32 v206, v205
	s_nop 1
	v_permlane32_swap_b32_e32 v203, v204
	v_permlane32_swap_b32_e32 v205, v206
	v_max_f32_e32 v204, v203, v204
	v_max_f32_e32 v203, v205, v206
	v_max_f32_e32 v205, v204, v203
	v_cmp_lt_f32_e32 vcc, s82, v205
	s_cmp_lg_u64 s[64:65], 0
	s_cbranch_scc1 .Lhwat1_firstchk
	s_cbranch_vccz .LBB0_2121
	s_branch .Lhwat1_rare
.Lhwat1_firstchk:
	v_min_f32_e32 v205, v204, v203
	v_cmp_gt_f32_e64 s[34:35], s83, v205
	s_or_b64 s[30:31], vcc, s[34:35]
	s_and_b64 vcc, exec, s[30:31]
	s_cbranch_vccz .LBB0_2121

.LBB0_2121:
	v_lshl_add_u32 v203, s68, 6, v202
	v_exp_f32_e32 v209, v80
	v_exp_f32_e32 v211, v81
	v_exp_f32_e32 v213, v82
	v_exp_f32_e32 v215, v83
	ds_read_b128 v[80:83], v203 offset:13312
	ds_read_b128 v[204:207], v203 offset:17920
	v_exp_f32_e32 v217, v84
	v_exp_f32_e32 v219, v85
	v_exp_f32_e32 v221, v86
	v_exp_f32_e32 v223, v87
	v_exp_f32_e32 v208, v64
	v_exp_f32_e32 v210, v65
	v_exp_f32_e32 v212, v66
	v_exp_f32_e32 v214, v67
	v_exp_f32_e32 v216, v68
	v_exp_f32_e32 v218, v69
	v_exp_f32_e32 v220, v70
	v_exp_f32_e32 v222, v71
	v_cvt_pk_bf16_f32 v64, v209, v211
	v_cvt_pk_bf16_f32 v65, v213, v215
	v_cvt_pk_bf16_f32 v66, v217, v219
	v_cvt_pk_bf16_f32 v67, v221, v223
	v_cvt_pk_bf16_f32 v68, v208, v210
	v_cvt_pk_bf16_f32 v69, v212, v214
	v_cvt_pk_bf16_f32 v70, v216, v218
	v_cvt_pk_bf16_f32 v71, v220, v222
	ds_read_b128 v[84:87], v203 offset:13344
	s_waitcnt lgkmcnt(0)
	v_mfma_f32_32x32x16_bf16 v[48:63], v[80:83], v[64:67], v[48:63]
	v_exp_f32_e32 v225, v88
	v_exp_f32_e32 v224, v72
	v_exp_f32_e32 v88, v73
	v_exp_f32_e32 v89, v89
	v_exp_f32_e32 v227, v90
	v_exp_f32_e32 v91, v91
	v_exp_f32_e32 v229, v92
	v_mfma_f32_32x32x16_bf16 v[16:31], v[80:83], v[68:71], v[16:31]
	ds_read_b128 v[80:83], v203 offset:17952
	v_exp_f32_e32 v93, v93
	v_exp_f32_e32 v231, v94
	v_exp_f32_e32 v95, v95
	v_exp_f32_e32 v226, v74
	v_exp_f32_e32 v90, v75
	v_exp_f32_e32 v228, v76
	v_mfma_f32_32x32x16_bf16 v[32:47], v[204:207], v[64:67], v[32:47]
	v_exp_f32_e32 v92, v77
	v_add_f32_e32 v64, v210, v208
	v_add_f32_e32 v65, v211, v209
	v_exp_f32_e32 v230, v78
	v_add_f32_e32 v208, v212, v64
	v_add_f32_e32 v209, v213, v65
	v_exp_f32_e32 v94, v79
	v_add_f32_e32 v72, v214, v208
	v_add_f32_e32 v73, v215, v209
	v_mfma_f32_32x32x16_bf16 v[0:15], v[204:207], v[68:71], v[0:15]
	v_add_f32_e64 v72, v216, v72
	v_add_f32_e64 v73, v217, v73
	v_cvt_pk_bf16_f32 v64, v225, v89
	v_add_f32_e64 v72, v218, v72
	v_add_f32_e64 v73, v219, v73
	v_cvt_pk_bf16_f32 v65, v227, v91
	v_add_f32_e32 v72, v220, v72
	v_add_f32_e32 v73, v221, v73
	v_cvt_pk_bf16_f32 v66, v229, v93
	v_add_f32_e32 v72, v222, v72
	v_add_f32_e32 v73, v223, v73
	v_cvt_pk_bf16_f32 v67, v231, v95
	v_cvt_pk_bf16_f32 v68, v224, v88
	v_cvt_pk_bf16_f32 v69, v226, v90
	v_cvt_pk_bf16_f32 v70, v228, v92
	v_cvt_pk_bf16_f32 v71, v230, v94
	v_add_f32_e32 v72, v224, v72
	v_add_f32_e32 v73, v225, v73
	v_mfma_f32_32x32x16_bf16 v[48:63], v[84:87], v[64:67], v[48:63]
	v_add_f32_e64 v72, v88, v72
	v_add_f32_e64 v73, v89, v73
	s_xor_b64 s[34:35], s[66:67], -1
	s_mov_b32 s68, 1
	s_mov_b64 s[66:67], 0
	s_and_b64 vcc, exec, s[34:35]
	v_mfma_f32_32x32x16_bf16 v[16:31], v[84:87], v[68:71], v[16:31]
	s_waitcnt lgkmcnt(0)
	v_mfma_f32_32x32x16_bf16 v[32:47], v[80:83], v[64:67], v[32:47]
	v_add_f32_e64 v64, v226, v72
	v_add_f32_e64 v65, v227, v73
	v_add_f32_e64 v64, v90, v64
	v_add_f32_e64 v65, v91, v65
	v_add_f32_e64 v64, v228, v64
	v_add_f32_e64 v65, v229, v65
	v_add_f32_e32 v64, v92, v64
	v_add_f32_e32 v65, v93, v65
	v_mfma_f32_32x32x16_bf16 v[0:15], v[80:83], v[68:71], v[0:15]
	v_add_f32_e64 v64, v230, v64
	v_add_f32_e64 v65, v231, v65
	v_add_f32_e64 v64, v94, v64
	v_add_f32_e64 v65, v95, v65
	v_add_f32_e64 v150, v150, v64
	v_add_f32_e64 v151, v151, v65
	s_cbranch_vccnz .LBB0_2123
	s_mov_b64 s[64:65], 0
	s_and_b64 vcc, exec, s[62:63]
	v_lshl_or_b32 v203, s68, 5, v190
	s_mov_b64 s[34:35], -1
	s_cbranch_vccz .LBB0_2116
	s_branch .LBB0_2117

	.amdhsa_kernel _Z14fwd_megakernel6Params
		.amdhsa_group_segment_fixed_size 65536
		.amdhsa_private_segment_fixed_size 0
		.amdhsa_kernarg_size 504
		.amdhsa_user_sgpr_count 2
		.amdhsa_user_sgpr_dispatch_ptr 0
		.amdhsa_user_sgpr_queue_ptr 0
		.amdhsa_user_sgpr_kernarg_segment_ptr 1
		.amdhsa_user_sgpr_dispatch_id 0
		.amdhsa_user_sgpr_kernarg_preload_length 0
		.amdhsa_user_sgpr_kernarg_preload_offset 0
		.amdhsa_user_sgpr_private_segment_size 0
		.amdhsa_uses_dynamic_stack 0
		.amdhsa_enable_private_segment 0
		.amdhsa_system_sgpr_workgroup_id_x 1
		.amdhsa_system_sgpr_workgroup_id_y 0
		.amdhsa_system_sgpr_workgroup_id_z 0
		.amdhsa_system_sgpr_workgroup_info 0
		.amdhsa_system_vgpr_workitem_id 2
		.amdhsa_next_free_vgpr 254
		.amdhsa_next_free_sgpr 102
		.amdhsa_accum_offset 256
		.amdhsa_reserve_vcc 1
		.amdhsa_float_round_mode_32 0
		.amdhsa_float_round_mode_16_64 0
		.amdhsa_float_denorm_mode_32 3
		.amdhsa_float_denorm_mode_16_64 3
		.amdhsa_dx10_clamp 1
		.amdhsa_ieee_mode 1
		.amdhsa_fp16_overflow 0
		.amdhsa_tg_split 0
		.amdhsa_exception_fp_ieee_invalid_op 0
		.amdhsa_exception_fp_denorm_src 0
		.amdhsa_exception_fp_ieee_div_zero 0
		.amdhsa_exception_fp_ieee_overflow 0
		.amdhsa_exception_fp_ieee_underflow 0
		.amdhsa_exception_fp_ieee_inexact 0
		.amdhsa_exception_int_div_zero 0
	.end_amdhsa_kernel

amdhsa.kernels:
  - .agpr_count:     0
    .args:
      - .offset:         0
        .size:           248
        .value_kind:     by_value
      - .offset:         248
        .size:           4
        .value_kind:     hidden_block_count_x
      - .offset:         252
        .size:           4
        .value_kind:     hidden_block_count_y
      - .offset:         256
        .size:           4
        .value_kind:     hidden_block_count_z
      - .offset:         260
        .size:           2
        .value_kind:     hidden_group_size_x
      - .offset:         262
        .size:           2
        .value_kind:     hidden_group_size_y
      - .offset:         264
        .size:           2
        .value_kind:     hidden_group_size_z
      - .offset:         266
        .size:           2
        .value_kind:     hidden_remainder_x
      - .offset:         268
        .size:           2
        .value_kind:     hidden_remainder_y
      - .offset:         270
        .size:           2
        .value_kind:     hidden_remainder_z
      - .offset:         288
        .size:           8
        .value_kind:     hidden_global_offset_x
      - .offset:         296
        .size:           8
        .value_kind:     hidden_global_offset_y
      - .offset:         304
        .size:           8
        .value_kind:     hidden_global_offset_z
      - .offset:         312
        .size:           2
        .value_kind:     hidden_grid_dims
      - .offset:         336
        .size:           8
        .value_kind:     hidden_multigrid_sync_arg
    .group_segment_fixed_size: 65536
    .kernarg_segment_align: 8
    .kernarg_segment_size: 504
    .language:       OpenCL C
    .language_version:
      - 2
      - 0
    .max_flat_workgroup_size: 256
    .name:           _Z14fwd_megakernel6Params
    .private_segment_fixed_size: 0
    .sgpr_count:     104
    .sgpr_spill_count: 4
    .symbol:         _Z14fwd_megakernel6Params.kd
    .uniform_work_group_size: 1
    .uses_dynamic_stack: false
    .vgpr_count:     254
    .vgpr_spill_count: 0
    .wavefront_size: 64
